# v49 + grid-barrier pollers use s_sleep 10
# baseline (speedup 1.0000x reference)
.LBB0_14:
	s_sleep 10
	global_load_dword v3, v0, s[2:3] offset:32 sc1
	s_waitcnt vmcnt(0)
	v_and_b32_e32 v3, 0xffff0000, v3
	v_cmp_ne_u32_e32 vcc, v3, v2
	s_or_b64 s[4:5], vcc, s[4:5]
	s_andn2_b64 exec, exec, s[4:5]
	s_cbranch_execnz .LBB0_14

.LBB0_115:
	global_load_dword v15, v16, s[4:5] sc1
	s_waitcnt lgkmcnt(0)
	global_load_dword v0, v16, s[6:7] sc1
	global_load_dword v1, v16, s[8:9] sc1
	global_load_dword v2, v16, s[10:11] sc1
	global_load_dword v3, v16, s[12:13] sc1
	global_load_dword v4, v16, s[14:15] sc1
	global_load_dword v5, v16, s[16:17] sc1
	global_load_dword v6, v16, s[18:19] sc1
	global_load_dword v7, v16, s[20:21] sc1
	global_load_dword v8, v16, s[22:23] sc1
	global_load_dword v9, v16, s[24:25] sc1
	global_load_dword v10, v16, s[26:27] sc1
	global_load_dword v11, v16, s[28:29] sc1
	global_load_dword v12, v16, s[30:31] sc1
	global_load_dword v13, v16, s[34:35] sc1
	global_load_dword v14, v16, s[36:37] sc1
	s_mov_b64 s[38:39], -1
	s_mov_b64 s[40:41], -1
	s_waitcnt vmcnt(14)
	v_add_u32_e32 v17, v0, v15
	s_waitcnt vmcnt(13)
	v_add_u32_e32 v17, v17, v1
	s_waitcnt vmcnt(12)
	v_add_u32_e32 v17, v17, v2
	s_waitcnt vmcnt(11)
	v_add_u32_e32 v17, v17, v3
	s_waitcnt vmcnt(10)
	v_add_u32_e32 v17, v17, v4
	s_waitcnt vmcnt(9)
	v_add_u32_e32 v17, v17, v5
	s_waitcnt vmcnt(8)
	v_add_u32_e32 v17, v17, v6
	s_waitcnt vmcnt(7)
	v_add_u32_e32 v17, v17, v7
	s_waitcnt vmcnt(6)
	v_add_u32_e32 v17, v17, v8
	s_waitcnt vmcnt(5)
	v_add_u32_e32 v17, v17, v9
	s_waitcnt vmcnt(4)
	v_add_u32_e32 v17, v17, v10
	s_waitcnt vmcnt(3)
	v_add_u32_e32 v17, v17, v11
	s_waitcnt vmcnt(2)
	v_add_u32_e32 v17, v17, v12
	s_waitcnt vmcnt(1)
	v_add_u32_e32 v17, v17, v13
	s_waitcnt vmcnt(0)
	v_add_u32_e32 v17, v17, v14
	v_cmp_eq_u32_e32 vcc, s33, v17
	s_cbranch_vccnz .LBB0_114
	s_and_b32 s38, s44, 0xff
	s_cmp_eq_u32 s38, 0
	s_mov_b64 s[38:39], -1
	s_mov_b64 s[42:43], -1
	s_sleep 10
	s_cbranch_scc0 .LBB0_119
	global_load_dword v17, v16, s[2:3] sc1
	s_waitcnt vmcnt(0)
	v_cmp_eq_u32_e32 vcc, 0, v17
	s_cbranch_vccnz .LBB0_121
	s_mov_b64 s[42:43], 0

.LBB0_133:
	s_and_b32 s18, s22, 0xff
	s_mov_b64 s[16:17], -1
	s_cmp_lg_u32 s18, 0
	s_mov_b64 s[20:21], -1
	s_sleep 10
	s_cbranch_scc1 .LBB0_136
	global_load_dword v2, v0, s[8:9] sc1
	s_waitcnt vmcnt(0)
	v_cmp_eq_u32_e32 vcc, 0, v2
	s_cbranch_vccnz .LBB0_138
	s_mov_b64 s[20:21], 0
	s_mov_b64 s[18:19], -1

.LBB0_150:
	s_and_b32 s16, s22, 0xff
	s_cmp_lg_u32 s16, 0
	s_mov_b64 s[18:19], -1
	s_sleep 10
	s_cbranch_scc1 .LBB0_153
	global_load_dword v1, v0, s[8:9] sc1
	s_waitcnt vmcnt(0)
	v_cmp_eq_u32_e32 vcc, 0, v1
	s_cbranch_vccnz .LBB0_155
	s_mov_b64 s[18:19], 0
	s_mov_b64 s[16:17], -1

.LBB0_571:
	global_load_dword v15, v16, s[6:7] sc1
	s_waitcnt lgkmcnt(0)
	global_load_dword v0, v16, s[8:9] sc1
	global_load_dword v1, v16, s[10:11] sc1
	global_load_dword v2, v16, s[12:13] sc1
	global_load_dword v3, v16, s[14:15] sc1
	global_load_dword v4, v16, s[16:17] sc1
	global_load_dword v5, v16, s[18:19] sc1
	global_load_dword v6, v16, s[20:21] sc1
	global_load_dword v7, v16, s[22:23] sc1
	global_load_dword v8, v16, s[24:25] sc1
	global_load_dword v9, v16, s[26:27] sc1
	global_load_dword v10, v16, s[28:29] sc1
	global_load_dword v11, v16, s[30:31] sc1
	global_load_dword v12, v16, s[34:35] sc1
	global_load_dword v13, v16, s[36:37] sc1
	global_load_dword v14, v16, s[38:39] sc1
	s_mov_b64 s[40:41], -1
	s_mov_b64 s[42:43], -1
	s_waitcnt vmcnt(14)
	v_add_u32_e32 v17, v0, v15
	s_waitcnt vmcnt(13)
	v_add_u32_e32 v17, v17, v1
	s_waitcnt vmcnt(12)
	v_add_u32_e32 v17, v17, v2
	s_waitcnt vmcnt(11)
	v_add_u32_e32 v17, v17, v3
	s_waitcnt vmcnt(10)
	v_add_u32_e32 v17, v17, v4
	s_waitcnt vmcnt(9)
	v_add_u32_e32 v17, v17, v5
	s_waitcnt vmcnt(8)
	v_add_u32_e32 v17, v17, v6
	s_waitcnt vmcnt(7)
	v_add_u32_e32 v17, v17, v7
	s_waitcnt vmcnt(6)
	v_add_u32_e32 v17, v17, v8
	s_waitcnt vmcnt(5)
	v_add_u32_e32 v17, v17, v9
	s_waitcnt vmcnt(4)
	v_add_u32_e32 v17, v17, v10
	s_waitcnt vmcnt(3)
	v_add_u32_e32 v17, v17, v11
	s_waitcnt vmcnt(2)
	v_add_u32_e32 v17, v17, v12
	s_waitcnt vmcnt(1)
	v_add_u32_e32 v17, v17, v13
	s_waitcnt vmcnt(0)
	v_add_u32_e32 v17, v17, v14
	v_cmp_eq_u32_e32 vcc, s33, v17
	s_cbranch_vccnz .LBB0_570
	s_and_b32 s40, s46, 0xff
	s_cmp_eq_u32 s40, 0
	s_mov_b64 s[40:41], -1
	s_mov_b64 s[44:45], -1
	s_sleep 10
	s_cbranch_scc0 .LBB0_575
	global_load_dword v17, v16, s[2:3] sc1
	s_waitcnt vmcnt(0)
	v_cmp_eq_u32_e32 vcc, 0, v17
	s_cbranch_vccnz .LBB0_577
	s_mov_b64 s[44:45], 0

.LBB0_589:
	s_and_b32 s20, s24, 0xff
	s_mov_b64 s[18:19], -1
	s_cmp_lg_u32 s20, 0
	s_mov_b64 s[22:23], -1
	s_sleep 10
	s_cbranch_scc1 .LBB0_592
	global_load_dword v2, v0, s[10:11] sc1
	s_waitcnt vmcnt(0)
	v_cmp_eq_u32_e32 vcc, 0, v2
	s_cbranch_vccnz .LBB0_594
	s_mov_b64 s[22:23], 0
	s_mov_b64 s[20:21], -1

.LBB0_606:
	s_and_b32 s18, s24, 0xff
	s_cmp_lg_u32 s18, 0
	s_mov_b64 s[20:21], -1
	s_sleep 10
	s_cbranch_scc1 .LBB0_609
	global_load_dword v1, v0, s[10:11] sc1
	s_waitcnt vmcnt(0)
	v_cmp_eq_u32_e32 vcc, 0, v1
	s_cbranch_vccnz .LBB0_611
	s_mov_b64 s[20:21], 0
	s_mov_b64 s[18:19], -1

.LBB0_658:
	global_load_dword v15, v16, s[12:13] sc1
	s_waitcnt lgkmcnt(0)
	global_load_dword v0, v16, s[14:15] sc1
	global_load_dword v1, v16, s[16:17] sc1
	global_load_dword v2, v16, s[18:19] sc1
	global_load_dword v3, v16, s[20:21] sc1
	global_load_dword v4, v16, s[22:23] sc1
	global_load_dword v5, v16, s[24:25] sc1
	global_load_dword v6, v16, s[26:27] sc1
	global_load_dword v7, v16, s[28:29] sc1
	global_load_dword v8, v16, s[30:31] sc1
	global_load_dword v9, v16, s[34:35] sc1
	global_load_dword v10, v16, s[36:37] sc1
	global_load_dword v11, v16, s[38:39] sc1
	global_load_dword v12, v16, s[40:41] sc1
	global_load_dword v13, v16, s[42:43] sc1
	global_load_dword v14, v16, s[44:45] sc1
	s_mov_b64 s[46:47], -1
	s_mov_b64 s[48:49], -1
	s_waitcnt vmcnt(14)
	v_add_u32_e32 v17, v0, v15
	s_waitcnt vmcnt(13)
	v_add_u32_e32 v17, v17, v1
	s_waitcnt vmcnt(12)
	v_add_u32_e32 v17, v17, v2
	s_waitcnt vmcnt(11)
	v_add_u32_e32 v17, v17, v3
	s_waitcnt vmcnt(10)
	v_add_u32_e32 v17, v17, v4
	s_waitcnt vmcnt(9)
	v_add_u32_e32 v17, v17, v5
	s_waitcnt vmcnt(8)
	v_add_u32_e32 v17, v17, v6
	s_waitcnt vmcnt(7)
	v_add_u32_e32 v17, v17, v7
	s_waitcnt vmcnt(6)
	v_add_u32_e32 v17, v17, v8
	s_waitcnt vmcnt(5)
	v_add_u32_e32 v17, v17, v9
	s_waitcnt vmcnt(4)
	v_add_u32_e32 v17, v17, v10
	s_waitcnt vmcnt(3)
	v_add_u32_e32 v17, v17, v11
	s_waitcnt vmcnt(2)
	v_add_u32_e32 v17, v17, v12
	s_waitcnt vmcnt(1)
	v_add_u32_e32 v17, v17, v13
	s_waitcnt vmcnt(0)
	v_add_u32_e32 v17, v17, v14
	v_cmp_eq_u32_e32 vcc, s52, v17
	s_cbranch_vccnz .LBB0_657
	s_and_b32 s46, s53, 0xff
	s_cmp_eq_u32 s46, 0
	s_mov_b64 s[46:47], -1
	s_mov_b64 s[50:51], -1
	s_sleep 10
	s_cbranch_scc0 .LBB0_662
	global_load_dword v17, v16, s[10:11] sc1
	s_waitcnt vmcnt(0)
	v_cmp_eq_u32_e32 vcc, 0, v17
	s_cbranch_vccnz .LBB0_664
	s_mov_b64 s[50:51], 0

.LBB0_676:
	s_and_b32 s26, s30, 0xff
	s_mov_b64 s[24:25], -1
	s_cmp_lg_u32 s26, 0
	s_mov_b64 s[28:29], -1
	s_sleep 10
	s_cbranch_scc1 .LBB0_679
	global_load_dword v2, v0, s[16:17] sc1
	s_waitcnt vmcnt(0)
	v_cmp_eq_u32_e32 vcc, 0, v2
	s_cbranch_vccnz .LBB0_681
	s_mov_b64 s[28:29], 0
	s_mov_b64 s[26:27], -1

.LBB0_693:
	s_and_b32 s24, s30, 0xff
	s_cmp_lg_u32 s24, 0
	s_mov_b64 s[26:27], -1
	s_sleep 10
	s_cbranch_scc1 .LBB0_696
	global_load_dword v1, v0, s[16:17] sc1
	s_waitcnt vmcnt(0)
	v_cmp_eq_u32_e32 vcc, 0, v1
	s_cbranch_vccnz .LBB0_698
	s_mov_b64 s[26:27], 0
	s_mov_b64 s[24:25], -1

.LBB0_848:
	global_load_dword v15, v16, s[6:7] sc1
	s_waitcnt lgkmcnt(0)
	global_load_dword v0, v16, s[8:9] sc1
	global_load_dword v1, v16, s[10:11] sc1
	global_load_dword v2, v16, s[16:17] sc1
	global_load_dword v3, v16, s[18:19] sc1
	global_load_dword v4, v16, s[20:21] sc1
	global_load_dword v5, v16, s[22:23] sc1
	global_load_dword v6, v16, s[24:25] sc1
	global_load_dword v7, v16, s[26:27] sc1
	global_load_dword v8, v16, s[28:29] sc1
	global_load_dword v9, v16, s[30:31] sc1
	global_load_dword v10, v16, s[34:35] sc1
	global_load_dword v11, v16, s[36:37] sc1
	global_load_dword v12, v16, s[38:39] sc1
	global_load_dword v13, v16, s[40:41] sc1
	global_load_dword v14, v16, s[42:43] sc1
	s_mov_b64 s[44:45], -1
	s_mov_b64 s[46:47], -1
	s_waitcnt vmcnt(14)
	v_add_u32_e32 v17, v0, v15
	s_waitcnt vmcnt(13)
	v_add_u32_e32 v17, v17, v1
	s_waitcnt vmcnt(12)
	v_add_u32_e32 v17, v17, v2
	s_waitcnt vmcnt(11)
	v_add_u32_e32 v17, v17, v3
	s_waitcnt vmcnt(10)
	v_add_u32_e32 v17, v17, v4
	s_waitcnt vmcnt(9)
	v_add_u32_e32 v17, v17, v5
	s_waitcnt vmcnt(8)
	v_add_u32_e32 v17, v17, v6
	s_waitcnt vmcnt(7)
	v_add_u32_e32 v17, v17, v7
	s_waitcnt vmcnt(6)
	v_add_u32_e32 v17, v17, v8
	s_waitcnt vmcnt(5)
	v_add_u32_e32 v17, v17, v9
	s_waitcnt vmcnt(4)
	v_add_u32_e32 v17, v17, v10
	s_waitcnt vmcnt(3)
	v_add_u32_e32 v17, v17, v11
	s_waitcnt vmcnt(2)
	v_add_u32_e32 v17, v17, v12
	s_waitcnt vmcnt(1)
	v_add_u32_e32 v17, v17, v13
	s_waitcnt vmcnt(0)
	v_add_u32_e32 v17, v17, v14
	v_cmp_eq_u32_e32 vcc, s33, v17
	s_cbranch_vccnz .LBB0_847
	s_and_b32 s44, s50, 0xff
	s_cmp_eq_u32 s44, 0
	s_mov_b64 s[44:45], -1
	s_mov_b64 s[48:49], -1
	s_sleep 10
	s_cbranch_scc0 .LBB0_852
	global_load_dword v17, v16, s[4:5] sc1
	s_waitcnt vmcnt(0)
	v_cmp_eq_u32_e32 vcc, 0, v17
	s_cbranch_vccnz .LBB0_854
	s_mov_b64 s[48:49], 0

.LBB0_866:
	s_and_b32 s24, s28, 0xff
	s_mov_b64 s[22:23], -1
	s_cmp_lg_u32 s24, 0
	s_mov_b64 s[26:27], -1
	s_sleep 10
	s_cbranch_scc1 .LBB0_869
	global_load_dword v2, v0, s[10:11] sc1
	s_waitcnt vmcnt(0)
	v_cmp_eq_u32_e32 vcc, 0, v2
	s_cbranch_vccnz .LBB0_871
	s_mov_b64 s[26:27], 0
	s_mov_b64 s[24:25], -1

.LBB0_883:
	s_and_b32 s22, s28, 0xff
	s_cmp_lg_u32 s22, 0
	s_mov_b64 s[24:25], -1
	s_sleep 10
	s_cbranch_scc1 .LBB0_886
	global_load_dword v1, v0, s[10:11] sc1
	s_waitcnt vmcnt(0)
	v_cmp_eq_u32_e32 vcc, 0, v1
	s_cbranch_vccnz .LBB0_888
	s_mov_b64 s[24:25], 0
	s_mov_b64 s[22:23], -1

.LBB0_956:
	global_load_dword v15, v16, s[6:7] sc1
	s_waitcnt lgkmcnt(0)
	global_load_dword v0, v16, s[8:9] sc1
	global_load_dword v1, v16, s[10:11] sc1
	global_load_dword v2, v16, s[16:17] sc1
	global_load_dword v3, v16, s[20:21] sc1
	global_load_dword v4, v16, s[22:23] sc1
	global_load_dword v5, v16, s[24:25] sc1
	global_load_dword v6, v16, s[26:27] sc1
	global_load_dword v7, v16, s[28:29] sc1
	global_load_dword v8, v16, s[30:31] sc1
	global_load_dword v9, v16, s[34:35] sc1
	global_load_dword v10, v16, s[36:37] sc1
	global_load_dword v11, v16, s[38:39] sc1
	global_load_dword v12, v16, s[40:41] sc1
	global_load_dword v13, v16, s[42:43] sc1
	global_load_dword v14, v16, s[44:45] sc1
	s_mov_b64 s[46:47], -1
	s_mov_b64 s[48:49], -1
	s_waitcnt vmcnt(14)
	v_add_u32_e32 v17, v0, v15
	s_waitcnt vmcnt(13)
	v_add_u32_e32 v17, v17, v1
	s_waitcnt vmcnt(12)
	v_add_u32_e32 v17, v17, v2
	s_waitcnt vmcnt(11)
	v_add_u32_e32 v17, v17, v3
	s_waitcnt vmcnt(10)
	v_add_u32_e32 v17, v17, v4
	s_waitcnt vmcnt(9)
	v_add_u32_e32 v17, v17, v5
	s_waitcnt vmcnt(8)
	v_add_u32_e32 v17, v17, v6
	s_waitcnt vmcnt(7)
	v_add_u32_e32 v17, v17, v7
	s_waitcnt vmcnt(6)
	v_add_u32_e32 v17, v17, v8
	s_waitcnt vmcnt(5)
	v_add_u32_e32 v17, v17, v9
	s_waitcnt vmcnt(4)
	v_add_u32_e32 v17, v17, v10
	s_waitcnt vmcnt(3)
	v_add_u32_e32 v17, v17, v11
	s_waitcnt vmcnt(2)
	v_add_u32_e32 v17, v17, v12
	s_waitcnt vmcnt(1)
	v_add_u32_e32 v17, v17, v13
	s_waitcnt vmcnt(0)
	v_add_u32_e32 v17, v17, v14
	v_cmp_eq_u32_e32 vcc, s33, v17
	s_cbranch_vccnz .LBB0_955
	s_and_b32 s46, s52, 0xff
	s_cmp_eq_u32 s46, 0
	s_mov_b64 s[46:47], -1
	s_mov_b64 s[50:51], -1
	s_sleep 10
	s_cbranch_scc0 .LBB0_960
	global_load_dword v17, v16, s[4:5] sc1
	s_waitcnt vmcnt(0)
	v_cmp_eq_u32_e32 vcc, 0, v17
	s_cbranch_vccnz .LBB0_962
	s_mov_b64 s[50:51], 0

.LBB0_974:
	s_and_b32 s26, s30, 0xff
	s_mov_b64 s[24:25], -1
	s_cmp_lg_u32 s26, 0
	s_mov_b64 s[28:29], -1
	s_sleep 10
	s_cbranch_scc1 .LBB0_977
	global_load_dword v2, v0, s[10:11] sc1
	s_waitcnt vmcnt(0)
	v_cmp_eq_u32_e32 vcc, 0, v2
	s_cbranch_vccnz .LBB0_979
	s_mov_b64 s[28:29], 0
	s_mov_b64 s[26:27], -1

.LBB0_991:
	s_and_b32 s24, s30, 0xff
	s_cmp_lg_u32 s24, 0
	s_mov_b64 s[26:27], -1
	s_sleep 10
	s_cbranch_scc1 .LBB0_994
	global_load_dword v1, v0, s[10:11] sc1
	s_waitcnt vmcnt(0)
	v_cmp_eq_u32_e32 vcc, 0, v1
	s_cbranch_vccnz .LBB0_996
	s_mov_b64 s[26:27], 0
	s_mov_b64 s[24:25], -1

.LBB0_1023:
	global_load_dword v15, v16, s[6:7] sc1
	s_waitcnt lgkmcnt(0)
	global_load_dword v0, v16, s[8:9] sc1
	global_load_dword v1, v16, s[10:11] sc1
	global_load_dword v2, v16, s[18:19] sc1
	global_load_dword v3, v16, s[20:21] sc1
	global_load_dword v4, v16, s[22:23] sc1
	global_load_dword v5, v16, s[24:25] sc1
	global_load_dword v6, v16, s[26:27] sc1
	global_load_dword v7, v16, s[28:29] sc1
	global_load_dword v8, v16, s[30:31] sc1
	global_load_dword v9, v16, s[34:35] sc1
	global_load_dword v10, v16, s[36:37] sc1
	global_load_dword v11, v16, s[38:39] sc1
	global_load_dword v12, v16, s[40:41] sc1
	global_load_dword v13, v16, s[42:43] sc1
	global_load_dword v14, v16, s[44:45] sc1
	s_mov_b64 s[46:47], -1
	s_mov_b64 s[48:49], -1
	s_waitcnt vmcnt(14)
	v_add_u32_e32 v17, v0, v15
	s_waitcnt vmcnt(13)
	v_add_u32_e32 v17, v17, v1
	s_waitcnt vmcnt(12)
	v_add_u32_e32 v17, v17, v2
	s_waitcnt vmcnt(11)
	v_add_u32_e32 v17, v17, v3
	s_waitcnt vmcnt(10)
	v_add_u32_e32 v17, v17, v4
	s_waitcnt vmcnt(9)
	v_add_u32_e32 v17, v17, v5
	s_waitcnt vmcnt(8)
	v_add_u32_e32 v17, v17, v6
	s_waitcnt vmcnt(7)
	v_add_u32_e32 v17, v17, v7
	s_waitcnt vmcnt(6)
	v_add_u32_e32 v17, v17, v8
	s_waitcnt vmcnt(5)
	v_add_u32_e32 v17, v17, v9
	s_waitcnt vmcnt(4)
	v_add_u32_e32 v17, v17, v10
	s_waitcnt vmcnt(3)
	v_add_u32_e32 v17, v17, v11
	s_waitcnt vmcnt(2)
	v_add_u32_e32 v17, v17, v12
	s_waitcnt vmcnt(1)
	v_add_u32_e32 v17, v17, v13
	s_waitcnt vmcnt(0)
	v_add_u32_e32 v17, v17, v14
	v_cmp_eq_u32_e32 vcc, s33, v17
	s_cbranch_vccnz .LBB0_1022
	s_and_b32 s46, s52, 0xff
	s_cmp_eq_u32 s46, 0
	s_mov_b64 s[46:47], -1
	s_mov_b64 s[50:51], -1
	s_sleep 10
	s_cbranch_scc0 .LBB0_1027
	global_load_dword v17, v16, s[4:5] sc1
	s_waitcnt vmcnt(0)
	v_cmp_eq_u32_e32 vcc, 0, v17
	s_cbranch_vccnz .LBB0_1029
	s_mov_b64 s[50:51], 0

.LBB0_1201:
	global_load_dword v15, v16, s[4:5] sc1
	s_waitcnt lgkmcnt(0)
	global_load_dword v0, v16, s[6:7] sc1
	global_load_dword v1, v16, s[8:9] sc1
	global_load_dword v2, v16, s[10:11] sc1
	global_load_dword v3, v16, s[16:17] sc1
	global_load_dword v4, v16, s[18:19] sc1
	global_load_dword v5, v16, s[20:21] sc1
	global_load_dword v6, v16, s[22:23] sc1
	global_load_dword v7, v16, s[24:25] sc1
	global_load_dword v8, v16, s[26:27] sc1
	global_load_dword v9, v16, s[28:29] sc1
	global_load_dword v10, v16, s[30:31] sc1
	global_load_dword v11, v16, s[34:35] sc1
	global_load_dword v12, v16, s[36:37] sc1
	global_load_dword v13, v16, s[38:39] sc1
	global_load_dword v14, v16, s[40:41] sc1
	s_mov_b64 s[42:43], -1
	s_mov_b64 s[44:45], -1
	s_waitcnt vmcnt(14)
	v_add_u32_e32 v17, v0, v15
	s_waitcnt vmcnt(13)
	v_add_u32_e32 v17, v17, v1
	s_waitcnt vmcnt(12)
	v_add_u32_e32 v17, v17, v2
	s_waitcnt vmcnt(11)
	v_add_u32_e32 v17, v17, v3
	s_waitcnt vmcnt(10)
	v_add_u32_e32 v17, v17, v4
	s_waitcnt vmcnt(9)
	v_add_u32_e32 v17, v17, v5
	s_waitcnt vmcnt(8)
	v_add_u32_e32 v17, v17, v6
	s_waitcnt vmcnt(7)
	v_add_u32_e32 v17, v17, v7
	s_waitcnt vmcnt(6)
	v_add_u32_e32 v17, v17, v8
	s_waitcnt vmcnt(5)
	v_add_u32_e32 v17, v17, v9
	s_waitcnt vmcnt(4)
	v_add_u32_e32 v17, v17, v10
	s_waitcnt vmcnt(3)
	v_add_u32_e32 v17, v17, v11
	s_waitcnt vmcnt(2)
	v_add_u32_e32 v17, v17, v12
	s_waitcnt vmcnt(1)
	v_add_u32_e32 v17, v17, v13
	s_waitcnt vmcnt(0)
	v_add_u32_e32 v17, v17, v14
	v_cmp_eq_u32_e32 vcc, s33, v17
	s_cbranch_vccnz .LBB0_1200
	s_and_b32 s42, s48, 0xff
	s_cmp_eq_u32 s42, 0
	s_mov_b64 s[42:43], -1
	s_mov_b64 s[46:47], -1
	s_sleep 10
	s_cbranch_scc0 .LBB0_1205
	global_load_dword v17, v16, s[2:3] sc1
	s_waitcnt vmcnt(0)
	v_cmp_eq_u32_e32 vcc, 0, v17
	s_cbranch_vccnz .LBB0_1207
	s_mov_b64 s[46:47], 0

.LBB0_1219:
	s_and_b32 s22, s26, 0xff
	s_mov_b64 s[20:21], -1
	s_cmp_lg_u32 s22, 0
	s_mov_b64 s[24:25], -1
	s_sleep 10
	s_cbranch_scc1 .LBB0_1222
	global_load_dword v2, v0, s[8:9] sc1
	s_waitcnt vmcnt(0)
	v_cmp_eq_u32_e32 vcc, 0, v2
	s_cbranch_vccnz .LBB0_1224
	s_mov_b64 s[24:25], 0
	s_mov_b64 s[22:23], -1

.LBB0_1236:
	s_and_b32 s20, s26, 0xff
	s_cmp_lg_u32 s20, 0
	s_mov_b64 s[22:23], -1
	s_sleep 10
	s_cbranch_scc1 .LBB0_1239
	global_load_dword v1, v0, s[8:9] sc1
	s_waitcnt vmcnt(0)
	v_cmp_eq_u32_e32 vcc, 0, v1
	s_cbranch_vccnz .LBB0_1241
	s_mov_b64 s[22:23], 0
	s_mov_b64 s[20:21], -1
